# v14 + attention unit order per workgroup changed to (15-s, s, 8+s, 7-s) so that sibling workgroups of a head start long units together (L2 sharing of K/V tiles)
# speedup vs baseline: 1.0125x; 1.0125x over previous
.LBB0_736:
	s_cmp_lt_i32 s41, 1
	s_mov_b32 s4, s60
	s_cbranch_scc1 .LBB0_741
	s_cmp_lg_u32 s41, 1
	s_mov_b64 s[8:9], -1
	s_cbranch_scc0 .LBB0_739
	s_cmp_eq_u32 s41, 2
	s_cselect_b32 s4, s55, s40
	s_mov_b64 s[8:9], 0
.LBB0_739:
	s_andn2_b64 vcc, exec, s[8:9]
	s_cbranch_vccnz .LBB0_741
	s_mov_b32 s4, s59
